# S5 table setup moved to the workgroups with a single gemv item; S5 recurrence: dropped the s_nop after plain v_fma asm blocks; XCC L2 invalidate issued right after the write-back
# speedup vs baseline: 1.0134x; 1.0025x over previous
.LBB0_21:
	s_sub_u32 s0, 0xff, s2
	s_lshl_b32 s0, s0, 9
	s_add_i32 s0, s93, s0
	v_add_u32_e32 v4, s0, v5
	s_movk_i32 s0, 0x2000
	v_cmp_gt_i32_e32 vcc, s0, v4
	s_and_saveexec_b64 s[10:11], vcc
	s_cbranch_execz .LBB0_30
	v_and_b32_e32 v0, 63, v5
	v_mov_b32_e32 v6, 0
	v_readlane_b32 s0, v252, 26
	v_lshlrev_b32_e32 v16, 5, v0
	v_mov_b32_e32 v17, v6
	v_readlane_b32 s1, v252, 27
	v_lshlrev_b32_e32 v20, 2, v0
	v_mov_b32_e32 v21, v6
	v_lshl_add_u64 v[8:9], s[0:1], 0, v[16:17]
	v_readlane_b32 s0, v252, 28
	v_readlane_b32 s1, v252, 29
	v_lshl_add_u64 v[12:13], s[94:95], 0, v[20:21]
	v_readlane_b32 s16, v252, 33
	v_lshl_add_u64 v[10:11], s[0:1], 0, v[20:21]
	s_mov_b64 s[0:1], 0x690000
	v_ashrrev_i32_e32 v5, 31, v4
	v_lshl_add_u64 v[14:15], v[12:13], 0, s[0:1]
	v_readlane_b32 s17, v252, 34
	v_readlane_b32 s18, v252, 35
	v_readlane_b32 s19, v252, 36
	v_readlane_b32 s20, v252, 37
	v_readlane_b32 s21, v252, 38
	v_readlane_b32 s22, v252, 39
	v_readlane_b32 s23, v252, 40
	v_readlane_b32 s24, v252, 41
	v_readlane_b32 s25, v252, 42
	v_readlane_b32 s26, v252, 43
	v_readlane_b32 s27, v252, 44
	v_readlane_b32 s28, v252, 45
	v_readlane_b32 s29, v252, 46
	v_readlane_b32 s30, v252, 47
	v_readlane_b32 s31, v252, 48
	v_lshlrev_b64 v[24:25], 6, v[4:5]
	s_mov_b32 s0, 0xeff8d898
	v_lshl_add_u64 v[18:19], s[20:21], 0, v[20:21]
	v_lshl_add_u64 v[20:21], s[22:23], 0, v[20:21]
	v_lshl_add_u64 v[22:23], s[18:19], 0, v[24:25]
	s_ashr_i32 s9, s8, 31
	v_lshl_add_u64 v[24:25], s[16:17], 0, v[24:25]
	s_mov_b32 s16, 0x652b82fe
	s_mov_b32 s18, 0xfee00000
	s_mov_b32 s20, 0x35793c76
	s_mov_b32 s1, 0x3e21eed8
	s_mov_b32 s22, 0x13a86d09
	s_mov_b32 s24, 0x67f544e4
	s_mov_b32 s26, 0xb7789f5c
	s_mov_b32 s28, 0xa556c734
	s_mov_b32 s30, 0x1a01a01a
	s_mov_b32 s36, 0x16c16c17
	s_mov_b32 s38, 0x11111111
	s_mov_b32 s40, 0x55555555
	s_mov_b32 s6, 0x6dc9c883
	s_mov_b32 s80, 0x54442d18
	s_mov_b32 s82, 0x33145c07
	s_mov_b32 s84, 0xa8c07c9d
	v_mov_b32_e32 v2, v0
	v_lshl_add_u64 v[16:17], s[94:95], 0, v[16:17]
	s_lshl_b64 s[12:13], s[8:9], 6
	s_mov_b64 s[14:15], 0
	s_mov_b32 s17, 0x3ff71547
	s_mov_b32 s19, 0xbfe62e42
	s_mov_b32 s21, 0xbdea39ef
	s_mov_b32 s23, 0x3de61246
	v_mov_b64_e32 v[26:27], s[0:1]
	s_mov_b32 s25, 0x3e5ae645
	s_mov_b32 s27, 0x3e927e4f
	s_mov_b32 s29, 0x3ec71de3
	s_mov_b32 s31, 0x3efa01a0
	s_mov_b32 s35, 0x3f2a01a0
	s_mov_b32 s34, s30
	s_mov_b32 s37, 0x3f56c16c
	s_mov_b32 s39, 0x3f811111
	s_mov_b32 s41, 0x3fa55555
	s_mov_b32 s43, 0x3fc55555
	s_mov_b32 s42, s40
	s_mov_b32 s7, 0x3fc45f30
	s_mov_b32 s81, 0xc01921fb
	s_mov_b32 s83, 0xbcb1a626
	s_mov_b32 s85, 0xbda93974
	s_mov_b32 s87, 0
	s_movk_i32 s9, 0x7fff
	s_mov_b32 s60, 0x7060302
	s_mov_b64 s[88:89], 0x200
	v_mov_b32_e32 v1, 0x3ff00000
	v_mov_b32_e32 v28, 0x67f544e4
	v_mov_b32_e32 v29, 0xbe5ae645
	v_mov_b32_e32 v30, 0x1a01a01a
	v_mov_b32_e32 v31, 0xbf2a01a0
	v_mov_b32_e32 v32, 0x55555555
	v_mov_b32_e32 v33, 0xbfc55555
	v_mov_b32_e32 v34, 0xb7789f5c
	v_mov_b32_e32 v35, 0xbe927e4f
	v_mov_b32_e32 v36, 0x16c16c17
	v_mov_b32_e32 v37, 0xbf56c16c
	v_mov_b32_e32 v3, 1
	s_branch .LBB0_24

.LBB0_324:
	v_lshlrev_b32_e32 v6, 16, v0
	v_and_b32_e32 v7, 0xffff0000, v0
	v_lshlrev_b32_e32 v0, 16, v1
	v_and_b32_e32 v1, 0xffff0000, v1
	s_waitcnt vmcnt(0)
	v_pk_fma_f32 v[116:117], v[4:5], v[0:1], v[70:71] op_sel_hi:[0,1,1]
	v_lshlrev_b32_e32 v0, 16, v2
	v_and_b32_e32 v1, 0xffff0000, v2
	v_pk_fma_f32 v[118:119], v[4:5], v[0:1], v[64:65] op_sel_hi:[0,1,1]
	v_lshlrev_b32_e32 v0, 16, v3
	v_and_b32_e32 v1, 0xffff0000, v3
	v_pk_fma_f32 v[114:115], v[4:5], v[6:7], v[68:69] op_sel_hi:[0,1,1]
	v_pk_fma_f32 v[120:121], v[4:5], v[0:1], v[66:67] op_sel_hi:[0,1,1]
	v_cvt_pk_bf16_f32 v122, v114, v115
	v_cvt_pk_bf16_f32 v123, v116, v117
	v_cvt_pk_bf16_f32 v124, v118, v119
	v_cvt_pk_bf16_f32 v125, v120, v121
	s_mov_b64 s[22:23], 0x1000
	v_lshl_add_u64 v[94:95], v[94:95], 0, s[22:23]
	v_mfma_f32_32x32x16_bf16 v[16:31], v[122:125], v[32:35], 0
	v_mfma_f32_32x32x16_bf16 v[0:15], v[122:125], v[36:39], 0
	ds_write_b128 v102, v[114:117] offset:27136
	ds_write_b128 v102, v[118:121] offset:27152
	s_nop 8
	ds_write_b128 v106, v[16:19]
	ds_write_b128 v106, v[20:23] offset:32
	ds_write_b128 v106, v[24:27] offset:64
	ds_write_b128 v106, v[28:31] offset:96
	ds_write_b128 v106, v[0:3] offset:4608
	v_mfma_f32_32x32x16_bf16 v[16:31], v[122:125], v[40:43], 0
	ds_write_b128 v106, v[4:7] offset:4640
	ds_write_b128 v106, v[8:11] offset:4672
	ds_write_b128 v106, v[12:15] offset:4704
	s_nop 8
	ds_write_b128 v106, v[16:19] offset:9216
	ds_write_b128 v106, v[20:23] offset:9248
	ds_write_b128 v106, v[24:27] offset:9280
	ds_write_b128 v106, v[28:31] offset:9312
	v_mfma_f32_32x32x16_bf16 v[0:15], v[122:125], v[44:47], 0
	s_nop 11
	ds_write_b128 v106, v[0:3] offset:13824
	ds_write_b128 v106, v[4:7] offset:13856
	ds_write_b128 v106, v[8:11] offset:13888
	ds_write_b128 v106, v[12:15] offset:13920
	s_waitcnt lgkmcnt(0)
	ds_read_b128 v[4:7], v107 offset:9216
	ds_read_b128 v[114:117], v107 offset:9232
	ds_read_b128 v[12:15], v107
	ds_read_b128 v[118:121], v107 offset:16
	ds_read_b128 v[122:125], v107 offset:32
	ds_read_b128 v[126:129], v107 offset:48
	ds_read_b128 v[130:133], v107 offset:9248
	ds_read_b128 v[134:137], v107 offset:9264
	ds_read_b128 v[28:31], v107 offset:64
	ds_read_b128 v[20:23], v107 offset:80
	ds_read_b128 v[24:27], v107 offset:9280
	ds_read_b128 v[16:19], v107 offset:9296
	ds_read_b128 v[8:11], v107 offset:96
	ds_read_b128 v[0:3], v107 offset:112
	s_waitcnt lgkmcnt(11)
	v_fma_f32 v12, -v93, v113, v12
	v_fma_f32 v4, v93, v112, v4
	v_fma_f32 v12, v92, v112, v12
	v_fma_f32 v4, v92, v113, v4
	v_fma_f32 v13, -v93, v4, v13
	v_fma_f32 v5, v93, v12, v5
	v_cvt_pk_bf16_f32 v112, v12, v4
	v_fma_f32 v113, v92, v12, v13
	v_fma_f32 v138, v92, v4, v5
	v_fma_f32 v4, -v93, v138, v14
	v_fma_f32 v5, v93, v113, v6
	v_fma_f32 v139, v92, v113, v4
	v_fma_f32 v140, v92, v138, v5
	v_cvt_pk_bf16_f32 v113, v113, v138
	v_add_u32_e32 v138, 0x4800, v108
	v_fma_f32 v141, -v93, v140, v15
	v_fma_f32 v142, v93, v139, v7
	ds_read_b128 v[12:15], v107 offset:9312
	ds_read_b128 v[4:7], v107 offset:9328
	ds_write2_b32 v138, v112, v113 offset1:68
	v_cvt_pk_bf16_f32 v112, v139, v140
	v_fma_f32 v113, v92, v139, v141
	v_fma_f32 v139, v92, v140, v142
	v_cvt_pk_bf16_f32 v140, v113, v139
	ds_write2_b32 v138, v112, v140 offset0:136 offset1:204
	s_waitcnt lgkmcnt(14)
	v_fma_f32 v112, -v93, v139, v118
	v_fma_f32 v114, v93, v113, v114
	v_fma_f32 v112, v92, v113, v112
	v_fma_f32 v113, v92, v139, v114
	v_fma_f32 v118, -v93, v113, v119
	v_fma_f32 v115, v93, v112, v115
	v_cvt_pk_bf16_f32 v114, v112, v113
	v_fma_f32 v112, v92, v112, v118
	v_fma_f32 v113, v92, v113, v115
	v_add_u32_e32 v118, 0x4c00, v108
	v_cvt_pk_bf16_f32 v115, v112, v113
	ds_write2_b32 v118, v114, v115 offset0:16 offset1:84
	v_fma_f32 v115, v93, v112, v116
	v_fma_f32 v114, -v93, v113, v120
	v_fma_f32 v112, v92, v112, v114
	v_fma_f32 v113, v92, v113, v115
	v_fma_f32 v115, -v93, v113, v121
	v_cvt_pk_bf16_f32 v114, v112, v113
	v_fma_f32 v116, v93, v112, v117
	v_fma_f32 v112, v92, v112, v115
	v_fma_f32 v113, v92, v113, v116
	v_cvt_pk_bf16_f32 v115, v112, v113
	ds_write2_b32 v118, v114, v115 offset0:152 offset1:220
	s_waitcnt lgkmcnt(13)
	v_fma_f32 v115, v93, v112, v130
	v_fma_f32 v114, -v93, v113, v122
	v_fma_f32 v112, v92, v112, v114
	v_fma_f32 v113, v92, v113, v115
	v_fma_f32 v115, -v93, v113, v123
	v_fma_f32 v116, v93, v112, v131
	v_cvt_pk_bf16_f32 v114, v112, v113
	v_fma_f32 v112, v92, v112, v115
	v_fma_f32 v113, v92, v113, v116
	v_add_u32_e32 v116, 0x5000, v108
	v_cvt_pk_bf16_f32 v115, v112, v113
	ds_write2_b32 v116, v114, v115 offset0:32 offset1:100
	v_fma_f32 v115, v93, v112, v132
	v_fma_f32 v114, -v93, v113, v124
	v_fma_f32 v112, v92, v112, v114
	v_fma_f32 v113, v92, v113, v115
	v_fma_f32 v115, -v93, v113, v125
	v_cvt_pk_bf16_f32 v114, v112, v113
	v_fma_f32 v117, v93, v112, v133
	v_fma_f32 v112, v92, v112, v115
	v_fma_f32 v113, v92, v113, v117
	v_cvt_pk_bf16_f32 v115, v112, v113
	ds_write2_b32 v116, v114, v115 offset0:168 offset1:236
	s_waitcnt lgkmcnt(14)
	v_fma_f32 v115, v93, v112, v134
	v_fma_f32 v114, -v93, v113, v126
	v_fma_f32 v112, v92, v112, v114
	v_fma_f32 v113, v92, v113, v115
	v_fma_f32 v115, -v93, v113, v127
	v_fma_f32 v116, v93, v112, v135
	v_cvt_pk_bf16_f32 v114, v112, v113
	v_fma_f32 v112, v92, v112, v115
	v_fma_f32 v113, v92, v113, v116
	v_add_u32_e32 v116, 0x5400, v108
	v_cvt_pk_bf16_f32 v115, v112, v113
	ds_write2_b32 v116, v114, v115 offset0:48 offset1:116
	v_fma_f32 v114, -v93, v113, v128
	v_fma_f32 v115, v93, v112, v136
	v_fma_f32 v112, v92, v112, v114
	v_fma_f32 v113, v92, v113, v115
	v_cvt_pk_bf16_f32 v114, v112, v113
	v_fma_f32 v115, -v93, v113, v129
	v_fma_f32 v117, v93, v112, v137
	v_fma_f32 v112, v92, v112, v115
	v_fma_f32 v113, v92, v113, v117
	s_waitcnt lgkmcnt(14)
	v_fma_f32 v28, -v93, v113, v28
	s_waitcnt lgkmcnt(12)
	v_fma_f32 v24, v93, v112, v24
	v_cvt_pk_bf16_f32 v115, v112, v113
	v_fma_f32 v28, v92, v112, v28
	v_fma_f32 v24, v92, v113, v24
	ds_write2_b32 v116, v114, v115 offset0:184 offset1:252
	v_fma_f32 v29, -v93, v24, v29
	v_fma_f32 v25, v93, v28, v25
	v_cvt_pk_bf16_f32 v112, v28, v24
	v_fma_f32 v28, v92, v28, v29
	v_fma_f32 v24, v92, v24, v25
	v_add_u32_e32 v29, 0x5800, v108
	v_cvt_pk_bf16_f32 v25, v28, v24
	ds_write2_b32 v29, v112, v25 offset0:64 offset1:132
	v_fma_f32 v25, -v93, v24, v30
	v_fma_f32 v26, v93, v28, v26
	v_fma_f32 v25, v92, v28, v25
	v_fma_f32 v24, v92, v24, v26
	v_cvt_pk_bf16_f32 v26, v25, v24
	v_fma_f32 v28, -v93, v24, v31
	v_fma_f32 v27, v93, v25, v27
	v_fma_f32 v25, v92, v25, v28
	v_fma_f32 v24, v92, v24, v27
	v_add_u32_e32 v28, 0x5a00, v108
	v_fma_f32 v20, -v93, v24, v20
	s_waitcnt lgkmcnt(13)
	v_fma_f32 v16, v93, v25, v16
	v_cvt_pk_bf16_f32 v27, v25, v24
	v_fma_f32 v20, v92, v25, v20
	v_fma_f32 v16, v92, v24, v16
	ds_write2_b32 v28, v26, v27 offset0:72 offset1:140
	v_fma_f32 v21, -v93, v16, v21
	v_fma_f32 v17, v93, v20, v17
	v_cvt_pk_bf16_f32 v24, v20, v16
	v_fma_f32 v20, v92, v20, v21
	v_fma_f32 v16, v92, v16, v17
	v_add_u32_e32 v21, 0x5c00, v108
	v_cvt_pk_bf16_f32 v17, v20, v16
	ds_write2_b32 v21, v24, v17 offset0:80 offset1:148
	v_fma_f32 v17, -v93, v16, v22
	v_fma_f32 v18, v93, v20, v18
	v_fma_f32 v17, v92, v20, v17
	v_fma_f32 v16, v92, v16, v18
	v_cvt_pk_bf16_f32 v18, v17, v16
	v_fma_f32 v20, -v93, v16, v23
	v_fma_f32 v19, v93, v17, v19
	v_fma_f32 v17, v92, v17, v20
	v_fma_f32 v16, v92, v16, v19
	v_add_u32_e32 v20, 0x5e00, v108
	s_waitcnt lgkmcnt(14)
	v_fma_f32 v8, -v93, v16, v8
	s_waitcnt lgkmcnt(12)
	v_fma_f32 v12, v93, v17, v12
	v_cvt_pk_bf16_f32 v19, v17, v16
	v_fma_f32 v8, v92, v17, v8
	v_fma_f32 v12, v92, v16, v12
	ds_write2_b32 v20, v18, v19 offset0:88 offset1:156
	v_fma_f32 v9, -v93, v12, v9
	v_fma_f32 v13, v93, v8, v13
	v_cvt_pk_bf16_f32 v16, v8, v12
	v_fma_f32 v8, v92, v8, v9
	v_fma_f32 v9, v92, v12, v13
	v_add_u32_e32 v13, 0x6000, v108
	v_cvt_pk_bf16_f32 v12, v8, v9
	ds_write2_b32 v13, v16, v12 offset0:96 offset1:164
	v_fma_f32 v10, -v93, v9, v10
	v_fma_f32 v12, v93, v8, v14
	v_fma_f32 v8, v92, v8, v10
	v_fma_f32 v9, v92, v9, v12
	v_cvt_pk_bf16_f32 v10, v8, v9
	v_fma_f32 v11, -v93, v9, v11
	v_fma_f32 v12, v93, v8, v15
	v_fma_f32 v8, v92, v8, v11
	v_fma_f32 v9, v92, v9, v12
	v_add_u32_e32 v12, 0x6200, v108
	v_fma_f32 v0, -v93, v9, v0
	s_waitcnt lgkmcnt(13)
	v_fma_f32 v4, v93, v8, v4
	v_cvt_pk_bf16_f32 v11, v8, v9
	v_fma_f32 v0, v92, v8, v0
	v_fma_f32 v4, v92, v9, v4
	ds_write2_b32 v12, v10, v11 offset0:104 offset1:172
	v_fma_f32 v1, -v93, v4, v1
	v_fma_f32 v5, v93, v0, v5
	v_cvt_pk_bf16_f32 v8, v0, v4
	v_fma_f32 v0, v92, v0, v1
	v_fma_f32 v1, v92, v4, v5
	v_add_u32_e32 v5, 0x6400, v108
	v_cvt_pk_bf16_f32 v4, v0, v1
	ds_write2_b32 v5, v8, v4 offset0:112 offset1:180
	v_fma_f32 v2, -v93, v1, v2
	v_fma_f32 v4, v93, v0, v6
	v_fma_f32 v0, v92, v0, v2
	v_fma_f32 v1, v92, v1, v4
	v_cvt_pk_bf16_f32 v2, v0, v1
	v_fma_f32 v3, -v93, v1, v3
	v_fma_f32 v4, v93, v0, v7
	v_fma_f32 v112, v92, v0, v3
	v_fma_f32 v113, v92, v1, v4
	v_add_u32_e32 v1, 0x6600, v108
	v_cvt_pk_bf16_f32 v0, v112, v113
	ds_write2_b32 v1, v2, v0 offset0:120 offset1:188
	s_waitcnt lgkmcnt(0)
	ds_read_b128 v[0:3], v103 offset:18432
	ds_read_b128 v[4:7], v103 offset:18496
	ds_read_b128 v[8:11], v103 offset:22784
	ds_read_b128 v[12:15], v103 offset:22848
	s_waitcnt lgkmcnt(3)
	v_mfma_f32_16x16x32_bf16 v[0:3], v[0:3], v[48:51], 0
	s_waitcnt lgkmcnt(1)
	v_mfma_f32_16x16x32_bf16 v[8:11], v[8:11], v[48:51], 0
	v_mfma_f32_16x16x32_bf16 v[0:3], v[4:7], v[52:55], v[0:3]
	s_waitcnt lgkmcnt(0)
	v_mfma_f32_16x16x32_bf16 v[4:7], v[12:15], v[52:55], v[8:11]
	s_nop 4
	ds_read_b128 v[8:11], v103 offset:18560
	ds_read_b128 v[12:15], v103 offset:18624
	s_waitcnt lgkmcnt(1)
	v_mfma_f32_16x16x32_bf16 v[0:3], v[8:11], v[56:59], v[0:3]
	ds_read_b128 v[8:11], v103 offset:22912
	ds_read_b128 v[16:19], v103 offset:22976
	s_waitcnt lgkmcnt(1)
	v_mfma_f32_16x16x32_bf16 v[4:7], v[8:11], v[56:59], v[4:7]
	v_add_u32_e32 v10, 0x6800, v109
	ds_read2_b32 v[8:9], v10 offset0:128 offset1:144
	v_mfma_f32_16x16x32_bf16 v[0:3], v[12:15], v[60:63], v[0:3]
	s_waitcnt lgkmcnt(1)
	v_mfma_f32_16x16x32_bf16 v[4:7], v[16:19], v[60:63], v[4:7]
	s_waitcnt lgkmcnt(0)
	s_nop 4
	v_pk_fma_f32 v[0:1], v[90:91], v[8:9], v[0:1]
	s_nop 0
	v_mul_f32_e32 v8, 0x3d372713, v0
	v_mul_f32_e32 v8, v0, v8
	v_fma_f32 v8, v0, v8, v0
	v_mul_f32_e32 v8, 0x3f4c422a, v8
	v_mul_f32_e32 v8, 0xc038aa3b, v8
	v_exp_f32_e32 v11, v8
	v_mul_f32_e32 v8, 0x3d372713, v1
	v_mul_f32_e32 v8, v1, v8
	v_fma_f32 v8, v1, v8, v1
	v_mul_f32_e32 v8, 0x3f4c422a, v8
	v_mul_f32_e32 v8, 0xc038aa3b, v8
	v_exp_f32_e32 v12, v8
	ds_read2_b32 v[8:9], v10 offset0:160 offset1:176
	v_add_f32_e32 v10, 1.0, v11
	v_rcp_f32_e32 v10, v10
	v_add_f32_e32 v11, 1.0, v12
	v_rcp_f32_e32 v11, v11
	s_waitcnt lgkmcnt(0)
	v_pk_fma_f32 v[2:3], v[90:91], v[8:9], v[2:3]
	v_add_u32_e32 v12, 0x6c00, v109
	v_mul_f32_e32 v8, 0x3d372713, v2
	v_mul_f32_e32 v9, 0x3d372713, v3
	v_mul_f32_e32 v8, v2, v8
	v_mul_f32_e32 v9, v3, v9
	v_fma_f32 v8, v2, v8, v2
	v_fma_f32 v9, v3, v9, v3
	v_mul_f32_e32 v8, 0x3f4c422a, v8
	v_mul_f32_e32 v9, 0x3f4c422a, v9
	v_mul_f32_e32 v8, 0xc038aa3b, v8
	v_mul_f32_e32 v9, 0xc038aa3b, v9
	v_exp_f32_e32 v8, v8
	v_exp_f32_e32 v9, v9
	v_pk_mul_f32 v[0:1], v[0:1], v[10:11]
	ds_read2_b32 v[10:11], v12 offset0:128 offset1:144
	v_add_f32_e32 v8, 1.0, v8
	v_add_f32_e32 v9, 1.0, v9
	v_rcp_f32_e32 v8, v8
	v_rcp_f32_e32 v9, v9
	s_nop 0
	v_pk_mul_f32 v[2:3], v[2:3], v[8:9]
	v_cvt_pk_bf16_f32 v8, v0, v1
	s_waitcnt lgkmcnt(0)
	v_pk_fma_f32 v[0:1], v[90:91], v[10:11], v[4:5]
	v_cvt_pk_bf16_f32 v9, v2, v3
	v_mul_f32_e32 v2, 0x3d372713, v0
	v_mul_f32_e32 v2, v0, v2
	v_fma_f32 v2, v0, v2, v0
	v_mul_f32_e32 v2, 0x3f4c422a, v2
	v_mul_f32_e32 v2, 0xc038aa3b, v2
	v_exp_f32_e32 v4, v2
	v_mul_f32_e32 v2, 0x3d372713, v1
	v_mul_f32_e32 v2, v1, v2
	v_fma_f32 v2, v1, v2, v1
	v_mul_f32_e32 v2, 0x3f4c422a, v2
	v_mul_f32_e32 v2, 0xc038aa3b, v2
	v_exp_f32_e32 v5, v2
	ds_read2_b32 v[2:3], v12 offset0:160 offset1:176
	v_add_f32_e32 v4, 1.0, v4
	v_rcp_f32_e32 v4, v4
	v_add_f32_e32 v5, 1.0, v5
	v_rcp_f32_e32 v5, v5
	s_waitcnt lgkmcnt(0)
	v_pk_fma_f32 v[2:3], v[90:91], v[2:3], v[6:7]
	ds_write_b16 v110, v8 offset:29184
	v_mul_f32_e32 v6, 0x3d372713, v2
	v_mul_f32_e32 v7, 0x3d372713, v3
	v_mul_f32_e32 v6, v2, v6
	v_mul_f32_e32 v7, v3, v7
	v_fma_f32 v6, v2, v6, v2
	v_fma_f32 v7, v3, v7, v3
	v_mul_f32_e32 v6, 0x3f4c422a, v6
	v_mul_f32_e32 v7, 0x3f4c422a, v7
	v_mul_f32_e32 v6, 0xc038aa3b, v6
	v_mul_f32_e32 v7, 0xc038aa3b, v7
	v_exp_f32_e32 v6, v6
	v_exp_f32_e32 v7, v7
	v_pk_mul_f32 v[0:1], v[0:1], v[4:5]
	ds_write_b16_d16_hi v110, v8 offset:29216
	v_add_f32_e32 v6, 1.0, v6
	v_add_f32_e32 v7, 1.0, v7
	v_rcp_f32_e32 v6, v6
	v_rcp_f32_e32 v7, v7
	v_cvt_pk_bf16_f32 v0, v0, v1
	ds_write_b16 v110, v9 offset:29248
	ds_write_b16_d16_hi v110, v9 offset:29280
	v_lshl_add_u64 v[4:5], v[96:97], 0, s[36:37]
	v_pk_mul_f32 v[2:3], v[2:3], v[6:7]
	s_add_u32 s36, s36, 0x10000
	v_cvt_pk_bf16_f32 v1, v2, v3
	ds_write_b16 v110, v0 offset:29696
	ds_write_b16_d16_hi v110, v0 offset:29728
	ds_write_b16 v110, v1 offset:29760
	ds_write_b16_d16_hi v110, v1 offset:29792
	s_waitcnt lgkmcnt(0)
	ds_read_b128 v[0:3], v104 offset:29184
	s_addc_u32 s37, s37, 0
	s_cmp_eq_u32 s36, 0x400000
	s_waitcnt lgkmcnt(0)
	global_store_dwordx4 v[4:5], v[0:3], off
	s_waitcnt lgkmcnt(0)
	s_nop 1
	v_mov_b64_e32 v[0:1], v[72:73]
	v_mov_b64_e32 v[2:3], v[74:75]
	v_mov_b32_e32 v4, v111
	s_cbranch_scc1 .LBB0_322

.Lxbar:
	s_add_u32 s101, s101, 1
	s_and_saveexec_b64 vcc, s[4:5]
	s_cbranch_execz .Lxbar_done
	v_mov_b32_e32 v0, 0x27fc0
	ds_read_b64 v[2:3], v0
	s_getreg_b32 s99, hwreg(HW_REG_XCC_ID, 0, 4)
	s_lshl_b32 s99, s99, 8
	s_add_u32 s100, s99, 0x1400
	v_mov_b32_e32 v1, s100
	s_add_u32 s100, s99, 0x4000
	v_mov_b32_e32 v7, s100
	s_add_u32 s100, s99, 0x5000
	v_mov_b32_e32 v8, s100
	v_mov_b32_e32 v4, 1
	global_atomic_add v5, v1, v4, s[94:95] sc0
	s_waitcnt vmcnt(0) lgkmcnt(0)
	v_readfirstlane_b32 s4, v2
	v_readfirstlane_b32 s5, v3
	v_readfirstlane_b32 s100, v5
	s_nop 3
	s_add_u32 s99, s101, 1
	s_mul_i32 s4, s4, s99
	s_mul_i32 s5, s5, s101
	s_add_u32 s100, s100, 1
	s_cmp_lg_u32 s100, s4
	s_cbranch_scc1 .Lxbar_follow
	buffer_wbl2 sc1
	s_waitcnt vmcnt(0) lgkmcnt(0)
	buffer_inv sc1
	s_movk_i32 s99, 0x4000

	v_mov_b32_e32 v6, s99
	global_atomic_add v6, v4, s[94:95]
	s_addk_i32 s99, 0x100
	v_mov_b32_e32 v6, s99
	global_atomic_add v6, v4, s[94:95]
	s_addk_i32 s99, 0x100
	v_mov_b32_e32 v6, s99
	global_atomic_add v6, v4, s[94:95]
	s_addk_i32 s99, 0x100
	v_mov_b32_e32 v6, s99
	global_atomic_add v6, v4, s[94:95]
	s_addk_i32 s99, 0x100
	v_mov_b32_e32 v6, s99
	global_atomic_add v6, v4, s[94:95]
	s_addk_i32 s99, 0x100
	v_mov_b32_e32 v6, s99
	global_atomic_add v6, v4, s[94:95]
	s_addk_i32 s99, 0x100
	v_mov_b32_e32 v6, s99
	global_atomic_add v6, v4, s[94:95]
	s_addk_i32 s99, 0x100
	v_mov_b32_e32 v6, s99
	global_atomic_add v6, v4, s[94:95]
	s_addk_i32 s99, 0x100
	v_mov_b32_e32 v6, s99
	global_atomic_add v6, v4, s[94:95]
	s_addk_i32 s99, 0x100
	v_mov_b32_e32 v6, s99
	global_atomic_add v6, v4, s[94:95]
	s_addk_i32 s99, 0x100
	v_mov_b32_e32 v6, s99
	global_atomic_add v6, v4, s[94:95]
	s_addk_i32 s99, 0x100
	v_mov_b32_e32 v6, s99
	global_atomic_add v6, v4, s[94:95]
	s_addk_i32 s99, 0x100
	v_mov_b32_e32 v6, s99
	global_atomic_add v6, v4, s[94:95]
	s_addk_i32 s99, 0x100
	v_mov_b32_e32 v6, s99
	global_atomic_add v6, v4, s[94:95]
	s_addk_i32 s99, 0x100
	v_mov_b32_e32 v6, s99
	global_atomic_add v6, v4, s[94:95]
	s_addk_i32 s99, 0x100
	v_mov_b32_e32 v6, s99
	global_atomic_add v6, v4, s[94:95]
	s_mov_b32 s99, 0

.Lxbar_rel:
	s_waitcnt vmcnt(0)
	global_atomic_add v8, v4, s[94:95]
	s_branch .Lxbar_done
